# cooperative grid.sync after the prologue replaced by the per-XCD last-arriver barrier
# speedup vs baseline: 1.0038x; 1.0033x over previous
; __global__ void __launch_bounds__(512) mega(Params p) {
;     ...
;   grid.sync();
.LBB0_222:
	s_waitcnt vmcnt(0)
	v_lshrrev_b32_e32 v2, 20, v0
	v_lshrrev_b32_e32 v0, 10, v0
	v_or_b32_e32 v0, v0, v2
	s_movk_i32 s2, 0x3ff
	v_and_or_b32 v0, v0, s2, v1
	v_cmp_eq_u32_e32 vcc, 0, v0
	s_barrier
	s_and_saveexec_b64 s[2:3], vcc
	s_cbranch_execz .LBB0_232
	v_readlane_b32 s4, v252, 42
	v_readlane_b32 s5, v252, 43
	s_nop 0
	s_add_u32 s4, s4, 0x1f414000
	s_addc_u32 s5, s5, 0
	s_getreg_b32 s6, hwreg(HW_REG_XCC_ID, 0, 4)
	s_lshl_b32 s6, s6, 2
	s_add_u32 s6, s4, s6
	s_addc_u32 s7, s5, 0
	v_mov_b32_e32 v0, 0
	v_mov_b32_e32 v1, 1
	global_atomic_add v1, v0, v1, s[6:7] offset:192 sc0
	s_waitcnt vmcnt(0)
	v_readfirstlane_b32 s0, v1
	s_cmp_lg_u32 s0, 31
	s_cbranch_scc1 .Lgs_spin
	buffer_wbl2 sc1
	s_waitcnt vmcnt(0)
	v_mov_b32_e32 v1, 1
	global_atomic_add v0, v1, s[4:5] offset:4
.Lgs_spin:
	global_load_dword v1, v0, s[4:5] offset:4 sc1
	s_waitcnt vmcnt(0)
	v_cmp_gt_u32_e32 vcc, 8, v1
	s_cbranch_vccnz .Lgs_spin
	buffer_inv sc1
	s_waitcnt vmcnt(0)
